# strategy 7.4 other half: one static s_setprio 1 for waves 0-3, set once at kernel entry
# speedup vs baseline: 1.0049x; 1.0004x over previous
.LBB0_5:
	s_or_b64 exec, exec, s[4:5]
	v_readfirstlane_b32 s4, v137
	s_nop 3
	s_lshr_b32 s4, s4, 6
	s_cmp_ge_u32 s4, 4
	s_cbranch_scc1 .Lprio_done
	s_setprio 1
